# phase 10 (ff2 layer 0) latent rows: hand-written 128x256-tile GEMM, B by LDS-DMA ring, A fragments loaded directly into registers
# speedup vs baseline: 1.0099x; 1.0025x over previous
.LBB0_1063:
	s_cmpk_gt_u32 s74, 0x1ff
	s_cbranch_scc1 .Lff2a_done
	s_and_b32 s6, s74, 7
	s_lshr_b32 s7, s74, 3
	s_lshl_b32 s6, s6, 4
	s_lshr_b32 s8, s7, 2
	s_add_u32 s6, s6, s8
	s_and_b32 s7, s7, 3
	s_lshr_b32 s8, s6, 6
	s_and_b32 s9, s6, 63
	s_mul_i32 s10, s8, 0x42
	s_add_u32 s10, s10, s9
	s_add_u32 s10, s10, 2
	v_lshrrev_b32_e32 v132, 6, v144
	v_and_b32_e32 v133, 63, v144
	v_readfirstlane_b32 s11, v132
	v_and_b32_e32 v134, 15, v133
	v_lshrrev_b32_e32 v135, 4, v133
	v_lshrrev_b32_e32 v136, 3, v133
	v_and_b32_e32 v137, 7, v133
	s_lshl_b32 s12, s10, 7
	s_lshl_b32 s13, s11, 5
	s_add_u32 s12, s12, s13
	s_mul_i32 s13, s12, 0x2080
	s_add_u32 s44, s94, s13
	s_addc_u32 s45, s95, 0
	s_add_u32 s44, s44, 0x4510000
	s_addc_u32 s45, s45, 0
	v_mul_u32_u24_e32 v236, 0x2080, v134
	v_lshl_add_u32 v236, v135, 4, v236
	v_add_u32_e32 v237, 0x20800, v236
	s_lshl_b32 s12, s7, 8
	s_lshl_b32 s13, s11, 3
	s_add_u32 s12, s12, s13
	s_mul_i32 s13, s12, 0x2080
	s_add_u32 s46, s94, s13
	s_addc_u32 s47, s95, 0
	s_add_u32 s46, s46, 0x1910000
	s_addc_u32 s47, s47, 0
	v_xor_b32_e32 v138, v137, v136
	v_mul_u32_u24_e32 v228, 0x2080, v136
	v_lshl_add_u32 v228, v138, 4, v228
	v_add_u32_e32 v229, 0x41000, v228
	v_add_u32_e32 v230, 0x82000, v228
	v_add_u32_e32 v231, 0xc3000, v228
	v_add_u32_e32 v232, 0x104000, v228
	v_add_u32_e32 v233, 0x145000, v228
	v_add_u32_e32 v234, 0x186000, v228
	v_add_u32_e32 v235, 0x1c7000, v228
	v_and_b32_e32 v138, 7, v134
	v_xor_b32_e32 v138, v138, v135
	v_lshlrev_b32_e32 v238, 7, v134
	v_lshl_add_u32 v238, v138, 4, v238
	v_xor_b32_e32 v239, 64, v238
	s_lshl_b32 s50, s11, 10
	s_movk_i32 s51, 0x20
	s_lshl_b32 s12, s6, 7
	s_lshl_b32 s13, s11, 5
	s_add_u32 s12, s12, s13
	s_lshl_b32 s12, s12, 12
	s_lshl_b32 s13, s7, 10
	s_add_u32 s12, s12, s13
	s_add_u32 s52, s92, s12
	s_addc_u32 s53, s93, 0
	s_mul_i32 s12, s8, 0x6000
	s_add_u32 s12, s12, s13
	s_add_u32 s12, s12, 0x5000
	s_add_u32 s54, s94, s12
	s_addc_u32 s55, s95, 0
	s_mov_b32 m0, s50
	s_nop 0
	global_load_lds_dwordx4 v228, s[46:47]
	s_add_u32 m0, s50, 0x1000
	s_nop 0
	global_load_lds_dwordx4 v229, s[46:47]
	s_add_u32 m0, s50, 0x2000
	s_nop 0
	global_load_lds_dwordx4 v230, s[46:47]
	s_add_u32 m0, s50, 0x3000
	s_nop 0
	global_load_lds_dwordx4 v231, s[46:47]
	s_add_u32 m0, s50, 0x4000
	s_nop 0
	global_load_lds_dwordx4 v232, s[46:47]
	s_add_u32 m0, s50, 0x5000
	s_nop 0
	global_load_lds_dwordx4 v233, s[46:47]
	s_add_u32 m0, s50, 0x6000
	s_nop 0
	global_load_lds_dwordx4 v234, s[46:47]
	s_add_u32 m0, s50, 0x7000
	s_nop 0
	global_load_lds_dwordx4 v235, s[46:47]
	global_load_dwordx4 v[148:151], v236, s[44:45]
	global_load_dwordx4 v[152:155], v236, s[44:45] offset:64
	global_load_dwordx4 v[156:159], v237, s[44:45]
	global_load_dwordx4 v[160:163], v237, s[44:45] offset:64
	s_add_u32 s44, s44, 0x80
	s_addc_u32 s45, s45, 0
	s_add_u32 s46, s46, 0x80
	s_addc_u32 s47, s47, 0
	v_mov_b32_e32 v4, 0
	v_mov_b32_e32 v5, 0
	v_mov_b32_e32 v6, 0
	v_mov_b32_e32 v7, 0
	v_mov_b32_e32 v8, 0
	v_mov_b32_e32 v9, 0
	v_mov_b32_e32 v10, 0
	v_mov_b32_e32 v11, 0
	v_mov_b32_e32 v12, 0
	v_mov_b32_e32 v13, 0
	v_mov_b32_e32 v14, 0
	v_mov_b32_e32 v15, 0
	v_mov_b32_e32 v16, 0
	v_mov_b32_e32 v17, 0
	v_mov_b32_e32 v18, 0
	v_mov_b32_e32 v19, 0
	v_mov_b32_e32 v20, 0
	v_mov_b32_e32 v21, 0
	v_mov_b32_e32 v22, 0
	v_mov_b32_e32 v23, 0
	v_mov_b32_e32 v24, 0
	v_mov_b32_e32 v25, 0
	v_mov_b32_e32 v26, 0
	v_mov_b32_e32 v27, 0
	v_mov_b32_e32 v28, 0
	v_mov_b32_e32 v29, 0
	v_mov_b32_e32 v30, 0
	v_mov_b32_e32 v31, 0
	v_mov_b32_e32 v32, 0
	v_mov_b32_e32 v33, 0
	v_mov_b32_e32 v34, 0
	v_mov_b32_e32 v35, 0
	v_mov_b32_e32 v36, 0
	v_mov_b32_e32 v37, 0
	v_mov_b32_e32 v38, 0
	v_mov_b32_e32 v39, 0
	v_mov_b32_e32 v40, 0
	v_mov_b32_e32 v41, 0
	v_mov_b32_e32 v42, 0
	v_mov_b32_e32 v43, 0
	v_mov_b32_e32 v44, 0
	v_mov_b32_e32 v45, 0
	v_mov_b32_e32 v46, 0
	v_mov_b32_e32 v47, 0
	v_mov_b32_e32 v48, 0
	v_mov_b32_e32 v49, 0
	v_mov_b32_e32 v50, 0
	v_mov_b32_e32 v51, 0
	v_mov_b32_e32 v52, 0
	v_mov_b32_e32 v53, 0
	v_mov_b32_e32 v54, 0
	v_mov_b32_e32 v55, 0
	v_mov_b32_e32 v56, 0
	v_mov_b32_e32 v57, 0
	v_mov_b32_e32 v58, 0
	v_mov_b32_e32 v59, 0
	v_mov_b32_e32 v60, 0
	v_mov_b32_e32 v61, 0
	v_mov_b32_e32 v62, 0
	v_mov_b32_e32 v63, 0
	v_mov_b32_e32 v64, 0
	v_mov_b32_e32 v65, 0
	v_mov_b32_e32 v66, 0
	v_mov_b32_e32 v67, 0
	v_mov_b32_e32 v68, 0
	v_mov_b32_e32 v69, 0
	v_mov_b32_e32 v70, 0
	v_mov_b32_e32 v71, 0
	v_mov_b32_e32 v72, 0
	v_mov_b32_e32 v73, 0
	v_mov_b32_e32 v74, 0
	v_mov_b32_e32 v75, 0
	v_mov_b32_e32 v76, 0
	v_mov_b32_e32 v77, 0
	v_mov_b32_e32 v78, 0
	v_mov_b32_e32 v79, 0
	v_mov_b32_e32 v80, 0
	v_mov_b32_e32 v81, 0
	v_mov_b32_e32 v82, 0
	v_mov_b32_e32 v83, 0
	v_mov_b32_e32 v84, 0
	v_mov_b32_e32 v85, 0
	v_mov_b32_e32 v86, 0
	v_mov_b32_e32 v87, 0
	v_mov_b32_e32 v88, 0
	v_mov_b32_e32 v89, 0
	v_mov_b32_e32 v90, 0
	v_mov_b32_e32 v91, 0
	v_mov_b32_e32 v92, 0
	v_mov_b32_e32 v93, 0
	v_mov_b32_e32 v94, 0
	v_mov_b32_e32 v95, 0
	v_mov_b32_e32 v96, 0
	v_mov_b32_e32 v97, 0
	v_mov_b32_e32 v98, 0
	v_mov_b32_e32 v99, 0
	v_mov_b32_e32 v100, 0
	v_mov_b32_e32 v101, 0
	v_mov_b32_e32 v102, 0
	v_mov_b32_e32 v103, 0
	v_mov_b32_e32 v104, 0
	v_mov_b32_e32 v105, 0
	v_mov_b32_e32 v106, 0
	v_mov_b32_e32 v107, 0
	v_mov_b32_e32 v108, 0
	v_mov_b32_e32 v109, 0
	v_mov_b32_e32 v110, 0
	v_mov_b32_e32 v111, 0
	v_mov_b32_e32 v112, 0
	v_mov_b32_e32 v113, 0
	v_mov_b32_e32 v114, 0
	v_mov_b32_e32 v115, 0
	v_mov_b32_e32 v116, 0
	v_mov_b32_e32 v117, 0
	v_mov_b32_e32 v118, 0
	v_mov_b32_e32 v119, 0
	v_mov_b32_e32 v120, 0
	v_mov_b32_e32 v121, 0
	v_mov_b32_e32 v122, 0
	v_mov_b32_e32 v123, 0
	v_mov_b32_e32 v124, 0
	v_mov_b32_e32 v125, 0
	v_mov_b32_e32 v126, 0
	v_mov_b32_e32 v127, 0
	v_mov_b32_e32 v128, 0
	v_mov_b32_e32 v129, 0
	v_mov_b32_e32 v130, 0
	v_mov_b32_e32 v131, 0
.Lff2a_loop:
	s_waitcnt vmcnt(0)
	s_barrier
	s_add_u32 m0, s50, 0x8000
	ds_read_b128 v[180:183], v238 offset:0
	global_load_lds_dwordx4 v228, s[46:47]
	s_add_u32 m0, s50, 0x9000
	ds_read_b128 v[184:187], v238 offset:2048
	global_load_lds_dwordx4 v229, s[46:47]
	s_add_u32 m0, s50, 0xa000
	ds_read_b128 v[188:191], v238 offset:4096
	global_load_lds_dwordx4 v230, s[46:47]
	s_add_u32 m0, s50, 0xb000
	ds_read_b128 v[192:195], v238 offset:6144
	global_load_lds_dwordx4 v231, s[46:47]
	s_add_u32 m0, s50, 0xc000
	ds_read_b128 v[196:199], v238 offset:8192
	global_load_lds_dwordx4 v232, s[46:47]
	s_add_u32 m0, s50, 0xd000
	ds_read_b128 v[200:203], v238 offset:10240
	global_load_lds_dwordx4 v233, s[46:47]
	s_add_u32 m0, s50, 0xe000
	ds_read_b128 v[204:207], v238 offset:12288
	global_load_lds_dwordx4 v234, s[46:47]
	s_add_u32 m0, s50, 0xf000
	ds_read_b128 v[208:211], v238 offset:14336
	global_load_lds_dwordx4 v235, s[46:47]
	global_load_dwordx4 v[164:167], v236, s[44:45]
	global_load_dwordx4 v[168:171], v236, s[44:45] offset:64
	global_load_dwordx4 v[172:175], v237, s[44:45]
	global_load_dwordx4 v[176:179], v237, s[44:45] offset:64
	s_add_u32 s44, s44, 0x80
	s_addc_u32 s45, s45, 0
	s_add_u32 s46, s46, 0x80
	s_addc_u32 s47, s47, 0
	ds_read_b128 v[212:215], v238 offset:16384
	ds_read_b128 v[216:219], v238 offset:18432
	ds_read_b128 v[220:223], v238 offset:20480
	ds_read_b128 v[224:227], v238 offset:22528
	s_waitcnt lgkmcnt(11)
	v_mfma_f32_16x16x32_bf16 v[4:7], v[180:183], v[148:151], v[4:7]
	v_mfma_f32_16x16x32_bf16 v[68:71], v[180:183], v[156:159], v[68:71]
	ds_read_b128 v[180:183], v238 offset:24576
	s_waitcnt lgkmcnt(11)
	v_mfma_f32_16x16x32_bf16 v[8:11], v[184:187], v[148:151], v[8:11]
	v_mfma_f32_16x16x32_bf16 v[72:75], v[184:187], v[156:159], v[72:75]
	ds_read_b128 v[184:187], v238 offset:26624
	s_waitcnt lgkmcnt(11)
	v_mfma_f32_16x16x32_bf16 v[12:15], v[188:191], v[148:151], v[12:15]
	v_mfma_f32_16x16x32_bf16 v[76:79], v[188:191], v[156:159], v[76:79]
	ds_read_b128 v[188:191], v238 offset:28672
	s_waitcnt lgkmcnt(11)
	v_mfma_f32_16x16x32_bf16 v[16:19], v[192:195], v[148:151], v[16:19]
	v_mfma_f32_16x16x32_bf16 v[80:83], v[192:195], v[156:159], v[80:83]
	ds_read_b128 v[192:195], v238 offset:30720
	s_waitcnt lgkmcnt(11)
	v_mfma_f32_16x16x32_bf16 v[20:23], v[196:199], v[148:151], v[20:23]
	v_mfma_f32_16x16x32_bf16 v[84:87], v[196:199], v[156:159], v[84:87]
	ds_read_b128 v[196:199], v239 offset:0
	s_waitcnt lgkmcnt(11)
	v_mfma_f32_16x16x32_bf16 v[24:27], v[200:203], v[148:151], v[24:27]
	v_mfma_f32_16x16x32_bf16 v[88:91], v[200:203], v[156:159], v[88:91]
	ds_read_b128 v[200:203], v239 offset:2048
	s_waitcnt lgkmcnt(11)
	v_mfma_f32_16x16x32_bf16 v[28:31], v[204:207], v[148:151], v[28:31]
	v_mfma_f32_16x16x32_bf16 v[92:95], v[204:207], v[156:159], v[92:95]
	ds_read_b128 v[204:207], v239 offset:4096
	s_waitcnt lgkmcnt(11)
	v_mfma_f32_16x16x32_bf16 v[32:35], v[208:211], v[148:151], v[32:35]
	v_mfma_f32_16x16x32_bf16 v[96:99], v[208:211], v[156:159], v[96:99]
	ds_read_b128 v[208:211], v239 offset:6144
	s_waitcnt lgkmcnt(11)
	v_mfma_f32_16x16x32_bf16 v[36:39], v[212:215], v[148:151], v[36:39]
	v_mfma_f32_16x16x32_bf16 v[100:103], v[212:215], v[156:159], v[100:103]
	ds_read_b128 v[212:215], v239 offset:8192
	s_waitcnt lgkmcnt(11)
	v_mfma_f32_16x16x32_bf16 v[40:43], v[216:219], v[148:151], v[40:43]
	v_mfma_f32_16x16x32_bf16 v[104:107], v[216:219], v[156:159], v[104:107]
	ds_read_b128 v[216:219], v239 offset:10240
	s_waitcnt lgkmcnt(11)
	v_mfma_f32_16x16x32_bf16 v[44:47], v[220:223], v[148:151], v[44:47]
	v_mfma_f32_16x16x32_bf16 v[108:111], v[220:223], v[156:159], v[108:111]
	ds_read_b128 v[220:223], v239 offset:12288
	s_waitcnt lgkmcnt(11)
	v_mfma_f32_16x16x32_bf16 v[48:51], v[224:227], v[148:151], v[48:51]
	v_mfma_f32_16x16x32_bf16 v[112:115], v[224:227], v[156:159], v[112:115]
	ds_read_b128 v[224:227], v239 offset:14336
	s_waitcnt lgkmcnt(11)
	v_mfma_f32_16x16x32_bf16 v[52:55], v[180:183], v[148:151], v[52:55]
	v_mfma_f32_16x16x32_bf16 v[116:119], v[180:183], v[156:159], v[116:119]
	ds_read_b128 v[180:183], v239 offset:16384
	s_waitcnt lgkmcnt(11)
	v_mfma_f32_16x16x32_bf16 v[56:59], v[184:187], v[148:151], v[56:59]
	v_mfma_f32_16x16x32_bf16 v[120:123], v[184:187], v[156:159], v[120:123]
	ds_read_b128 v[184:187], v239 offset:18432
	s_waitcnt lgkmcnt(11)
	v_mfma_f32_16x16x32_bf16 v[60:63], v[188:191], v[148:151], v[60:63]
	v_mfma_f32_16x16x32_bf16 v[124:127], v[188:191], v[156:159], v[124:127]
	ds_read_b128 v[188:191], v239 offset:20480
	s_waitcnt lgkmcnt(11)
	v_mfma_f32_16x16x32_bf16 v[64:67], v[192:195], v[148:151], v[64:67]
	v_mfma_f32_16x16x32_bf16 v[128:131], v[192:195], v[156:159], v[128:131]
	ds_read_b128 v[192:195], v239 offset:22528
	s_waitcnt lgkmcnt(11)
	v_mfma_f32_16x16x32_bf16 v[4:7], v[196:199], v[152:155], v[4:7]
	v_mfma_f32_16x16x32_bf16 v[68:71], v[196:199], v[160:163], v[68:71]
	ds_read_b128 v[196:199], v239 offset:24576
	s_waitcnt lgkmcnt(11)
	v_mfma_f32_16x16x32_bf16 v[8:11], v[200:203], v[152:155], v[8:11]
	v_mfma_f32_16x16x32_bf16 v[72:75], v[200:203], v[160:163], v[72:75]
	ds_read_b128 v[200:203], v239 offset:26624
	s_waitcnt lgkmcnt(11)
	v_mfma_f32_16x16x32_bf16 v[12:15], v[204:207], v[152:155], v[12:15]
	v_mfma_f32_16x16x32_bf16 v[76:79], v[204:207], v[160:163], v[76:79]
	ds_read_b128 v[204:207], v239 offset:28672
	s_waitcnt lgkmcnt(11)
	v_mfma_f32_16x16x32_bf16 v[16:19], v[208:211], v[152:155], v[16:19]
	v_mfma_f32_16x16x32_bf16 v[80:83], v[208:211], v[160:163], v[80:83]
	ds_read_b128 v[208:211], v239 offset:30720
	s_waitcnt lgkmcnt(11)
	v_mfma_f32_16x16x32_bf16 v[20:23], v[212:215], v[152:155], v[20:23]
	v_mfma_f32_16x16x32_bf16 v[84:87], v[212:215], v[160:163], v[84:87]
	s_waitcnt lgkmcnt(10)
	v_mfma_f32_16x16x32_bf16 v[24:27], v[216:219], v[152:155], v[24:27]
	v_mfma_f32_16x16x32_bf16 v[88:91], v[216:219], v[160:163], v[88:91]
	s_waitcnt lgkmcnt(9)
	v_mfma_f32_16x16x32_bf16 v[28:31], v[220:223], v[152:155], v[28:31]
	v_mfma_f32_16x16x32_bf16 v[92:95], v[220:223], v[160:163], v[92:95]
	s_waitcnt lgkmcnt(8)
	v_mfma_f32_16x16x32_bf16 v[32:35], v[224:227], v[152:155], v[32:35]
	v_mfma_f32_16x16x32_bf16 v[96:99], v[224:227], v[160:163], v[96:99]
	s_waitcnt lgkmcnt(7)
	v_mfma_f32_16x16x32_bf16 v[36:39], v[180:183], v[152:155], v[36:39]
	v_mfma_f32_16x16x32_bf16 v[100:103], v[180:183], v[160:163], v[100:103]
	s_waitcnt lgkmcnt(6)
	v_mfma_f32_16x16x32_bf16 v[40:43], v[184:187], v[152:155], v[40:43]
	v_mfma_f32_16x16x32_bf16 v[104:107], v[184:187], v[160:163], v[104:107]
	s_waitcnt lgkmcnt(5)
	v_mfma_f32_16x16x32_bf16 v[44:47], v[188:191], v[152:155], v[44:47]
	v_mfma_f32_16x16x32_bf16 v[108:111], v[188:191], v[160:163], v[108:111]
	s_waitcnt lgkmcnt(4)
	v_mfma_f32_16x16x32_bf16 v[48:51], v[192:195], v[152:155], v[48:51]
	v_mfma_f32_16x16x32_bf16 v[112:115], v[192:195], v[160:163], v[112:115]
	s_waitcnt lgkmcnt(3)
	v_mfma_f32_16x16x32_bf16 v[52:55], v[196:199], v[152:155], v[52:55]
	v_mfma_f32_16x16x32_bf16 v[116:119], v[196:199], v[160:163], v[116:119]
	s_waitcnt lgkmcnt(2)
	v_mfma_f32_16x16x32_bf16 v[56:59], v[200:203], v[152:155], v[56:59]
	v_mfma_f32_16x16x32_bf16 v[120:123], v[200:203], v[160:163], v[120:123]
	s_waitcnt lgkmcnt(1)
	v_mfma_f32_16x16x32_bf16 v[60:63], v[204:207], v[152:155], v[60:63]
	v_mfma_f32_16x16x32_bf16 v[124:127], v[204:207], v[160:163], v[124:127]
	s_waitcnt lgkmcnt(0)
	v_mfma_f32_16x16x32_bf16 v[64:67], v[208:211], v[152:155], v[64:67]
	v_mfma_f32_16x16x32_bf16 v[128:131], v[208:211], v[160:163], v[128:131]
	s_waitcnt vmcnt(0)
	s_barrier
	ds_read_b128 v[180:183], v238 offset:32768
	ds_read_b128 v[184:187], v238 offset:34816
	ds_read_b128 v[188:191], v238 offset:36864
	ds_read_b128 v[192:195], v238 offset:38912
	ds_read_b128 v[196:199], v238 offset:40960
	ds_read_b128 v[200:203], v238 offset:43008
	ds_read_b128 v[204:207], v238 offset:45056
	ds_read_b128 v[208:211], v238 offset:47104
	ds_read_b128 v[212:215], v238 offset:49152
	ds_read_b128 v[216:219], v238 offset:51200
	ds_read_b128 v[220:223], v238 offset:53248
	ds_read_b128 v[224:227], v238 offset:55296
	s_cmp_eq_u32 s51, 1
	s_cbranch_scc1 .Lff2a_last
	s_mov_b32 m0, s50
	s_nop 0
	global_load_lds_dwordx4 v228, s[46:47]
	s_add_u32 m0, s50, 0x1000
	s_nop 0
	global_load_lds_dwordx4 v229, s[46:47]
	s_add_u32 m0, s50, 0x2000
	s_nop 0
	global_load_lds_dwordx4 v230, s[46:47]
	s_add_u32 m0, s50, 0x3000
	s_nop 0
	global_load_lds_dwordx4 v231, s[46:47]
	s_add_u32 m0, s50, 0x4000
	s_nop 0
	global_load_lds_dwordx4 v232, s[46:47]
	s_add_u32 m0, s50, 0x5000
	s_nop 0
	global_load_lds_dwordx4 v233, s[46:47]
	s_add_u32 m0, s50, 0x6000
	s_nop 0
	global_load_lds_dwordx4 v234, s[46:47]
	s_add_u32 m0, s50, 0x7000
	s_nop 0
	global_load_lds_dwordx4 v235, s[46:47]
	global_load_dwordx4 v[148:151], v236, s[44:45]
	global_load_dwordx4 v[152:155], v236, s[44:45] offset:64
	global_load_dwordx4 v[156:159], v237, s[44:45]
	global_load_dwordx4 v[160:163], v237, s[44:45] offset:64
	s_add_u32 s44, s44, 0x80
	s_addc_u32 s45, s45, 0
	s_add_u32 s46, s46, 0x80
	s_addc_u32 s47, s47, 0
.Lff2a_last:
	s_waitcnt lgkmcnt(11)
	v_mfma_f32_16x16x32_bf16 v[4:7], v[180:183], v[164:167], v[4:7]
	v_mfma_f32_16x16x32_bf16 v[68:71], v[180:183], v[172:175], v[68:71]
	ds_read_b128 v[180:183], v238 offset:57344
	s_waitcnt lgkmcnt(11)
	v_mfma_f32_16x16x32_bf16 v[8:11], v[184:187], v[164:167], v[8:11]
	v_mfma_f32_16x16x32_bf16 v[72:75], v[184:187], v[172:175], v[72:75]
	ds_read_b128 v[184:187], v238 offset:59392
	s_waitcnt lgkmcnt(11)
	v_mfma_f32_16x16x32_bf16 v[12:15], v[188:191], v[164:167], v[12:15]
	v_mfma_f32_16x16x32_bf16 v[76:79], v[188:191], v[172:175], v[76:79]
	ds_read_b128 v[188:191], v238 offset:61440
	s_waitcnt lgkmcnt(11)
	v_mfma_f32_16x16x32_bf16 v[16:19], v[192:195], v[164:167], v[16:19]
	v_mfma_f32_16x16x32_bf16 v[80:83], v[192:195], v[172:175], v[80:83]
	ds_read_b128 v[192:195], v238 offset:63488
	s_waitcnt lgkmcnt(11)
	v_mfma_f32_16x16x32_bf16 v[20:23], v[196:199], v[164:167], v[20:23]
	v_mfma_f32_16x16x32_bf16 v[84:87], v[196:199], v[172:175], v[84:87]
	ds_read_b128 v[196:199], v239 offset:32768
	s_waitcnt lgkmcnt(11)
	v_mfma_f32_16x16x32_bf16 v[24:27], v[200:203], v[164:167], v[24:27]
	v_mfma_f32_16x16x32_bf16 v[88:91], v[200:203], v[172:175], v[88:91]
	ds_read_b128 v[200:203], v239 offset:34816
	s_waitcnt lgkmcnt(11)
	v_mfma_f32_16x16x32_bf16 v[28:31], v[204:207], v[164:167], v[28:31]
	v_mfma_f32_16x16x32_bf16 v[92:95], v[204:207], v[172:175], v[92:95]
	ds_read_b128 v[204:207], v239 offset:36864
	s_waitcnt lgkmcnt(11)
	v_mfma_f32_16x16x32_bf16 v[32:35], v[208:211], v[164:167], v[32:35]
	v_mfma_f32_16x16x32_bf16 v[96:99], v[208:211], v[172:175], v[96:99]
	ds_read_b128 v[208:211], v239 offset:38912
	s_waitcnt lgkmcnt(11)
	v_mfma_f32_16x16x32_bf16 v[36:39], v[212:215], v[164:167], v[36:39]
	v_mfma_f32_16x16x32_bf16 v[100:103], v[212:215], v[172:175], v[100:103]
	ds_read_b128 v[212:215], v239 offset:40960
	s_waitcnt lgkmcnt(11)
	v_mfma_f32_16x16x32_bf16 v[40:43], v[216:219], v[164:167], v[40:43]
	v_mfma_f32_16x16x32_bf16 v[104:107], v[216:219], v[172:175], v[104:107]
	ds_read_b128 v[216:219], v239 offset:43008
	s_waitcnt lgkmcnt(11)
	v_mfma_f32_16x16x32_bf16 v[44:47], v[220:223], v[164:167], v[44:47]
	v_mfma_f32_16x16x32_bf16 v[108:111], v[220:223], v[172:175], v[108:111]
	ds_read_b128 v[220:223], v239 offset:45056
	s_waitcnt lgkmcnt(11)
	v_mfma_f32_16x16x32_bf16 v[48:51], v[224:227], v[164:167], v[48:51]
	v_mfma_f32_16x16x32_bf16 v[112:115], v[224:227], v[172:175], v[112:115]
	ds_read_b128 v[224:227], v239 offset:47104
	s_waitcnt lgkmcnt(11)
	v_mfma_f32_16x16x32_bf16 v[52:55], v[180:183], v[164:167], v[52:55]
	v_mfma_f32_16x16x32_bf16 v[116:119], v[180:183], v[172:175], v[116:119]
	ds_read_b128 v[180:183], v239 offset:49152
	s_waitcnt lgkmcnt(11)
	v_mfma_f32_16x16x32_bf16 v[56:59], v[184:187], v[164:167], v[56:59]
	v_mfma_f32_16x16x32_bf16 v[120:123], v[184:187], v[172:175], v[120:123]
	ds_read_b128 v[184:187], v239 offset:51200
	s_waitcnt lgkmcnt(11)
	v_mfma_f32_16x16x32_bf16 v[60:63], v[188:191], v[164:167], v[60:63]
	v_mfma_f32_16x16x32_bf16 v[124:127], v[188:191], v[172:175], v[124:127]
	ds_read_b128 v[188:191], v239 offset:53248
	s_waitcnt lgkmcnt(11)
	v_mfma_f32_16x16x32_bf16 v[64:67], v[192:195], v[164:167], v[64:67]
	v_mfma_f32_16x16x32_bf16 v[128:131], v[192:195], v[172:175], v[128:131]
	ds_read_b128 v[192:195], v239 offset:55296
	s_waitcnt lgkmcnt(11)
	v_mfma_f32_16x16x32_bf16 v[4:7], v[196:199], v[168:171], v[4:7]
	v_mfma_f32_16x16x32_bf16 v[68:71], v[196:199], v[176:179], v[68:71]
	ds_read_b128 v[196:199], v239 offset:57344
	s_waitcnt lgkmcnt(11)
	v_mfma_f32_16x16x32_bf16 v[8:11], v[200:203], v[168:171], v[8:11]
	v_mfma_f32_16x16x32_bf16 v[72:75], v[200:203], v[176:179], v[72:75]
	ds_read_b128 v[200:203], v239 offset:59392
	s_waitcnt lgkmcnt(11)
	v_mfma_f32_16x16x32_bf16 v[12:15], v[204:207], v[168:171], v[12:15]
	v_mfma_f32_16x16x32_bf16 v[76:79], v[204:207], v[176:179], v[76:79]
	ds_read_b128 v[204:207], v239 offset:61440
	s_waitcnt lgkmcnt(11)
	v_mfma_f32_16x16x32_bf16 v[16:19], v[208:211], v[168:171], v[16:19]
	v_mfma_f32_16x16x32_bf16 v[80:83], v[208:211], v[176:179], v[80:83]
	ds_read_b128 v[208:211], v239 offset:63488
	s_waitcnt lgkmcnt(11)
	v_mfma_f32_16x16x32_bf16 v[20:23], v[212:215], v[168:171], v[20:23]
	v_mfma_f32_16x16x32_bf16 v[84:87], v[212:215], v[176:179], v[84:87]
	s_waitcnt lgkmcnt(10)
	v_mfma_f32_16x16x32_bf16 v[24:27], v[216:219], v[168:171], v[24:27]
	v_mfma_f32_16x16x32_bf16 v[88:91], v[216:219], v[176:179], v[88:91]
	s_waitcnt lgkmcnt(9)
	v_mfma_f32_16x16x32_bf16 v[28:31], v[220:223], v[168:171], v[28:31]
	v_mfma_f32_16x16x32_bf16 v[92:95], v[220:223], v[176:179], v[92:95]
	s_waitcnt lgkmcnt(8)
	v_mfma_f32_16x16x32_bf16 v[32:35], v[224:227], v[168:171], v[32:35]
	v_mfma_f32_16x16x32_bf16 v[96:99], v[224:227], v[176:179], v[96:99]
	s_waitcnt lgkmcnt(7)
	v_mfma_f32_16x16x32_bf16 v[36:39], v[180:183], v[168:171], v[36:39]
	v_mfma_f32_16x16x32_bf16 v[100:103], v[180:183], v[176:179], v[100:103]
	s_waitcnt lgkmcnt(6)
	v_mfma_f32_16x16x32_bf16 v[40:43], v[184:187], v[168:171], v[40:43]
	v_mfma_f32_16x16x32_bf16 v[104:107], v[184:187], v[176:179], v[104:107]
	s_waitcnt lgkmcnt(5)
	v_mfma_f32_16x16x32_bf16 v[44:47], v[188:191], v[168:171], v[44:47]
	v_mfma_f32_16x16x32_bf16 v[108:111], v[188:191], v[176:179], v[108:111]
	s_waitcnt lgkmcnt(4)
	v_mfma_f32_16x16x32_bf16 v[48:51], v[192:195], v[168:171], v[48:51]
	v_mfma_f32_16x16x32_bf16 v[112:115], v[192:195], v[176:179], v[112:115]
	s_waitcnt lgkmcnt(3)
	v_mfma_f32_16x16x32_bf16 v[52:55], v[196:199], v[168:171], v[52:55]
	v_mfma_f32_16x16x32_bf16 v[116:119], v[196:199], v[176:179], v[116:119]
	s_waitcnt lgkmcnt(2)
	v_mfma_f32_16x16x32_bf16 v[56:59], v[200:203], v[168:171], v[56:59]
	v_mfma_f32_16x16x32_bf16 v[120:123], v[200:203], v[176:179], v[120:123]
	s_waitcnt lgkmcnt(1)
	v_mfma_f32_16x16x32_bf16 v[60:63], v[204:207], v[168:171], v[60:63]
	v_mfma_f32_16x16x32_bf16 v[124:127], v[204:207], v[176:179], v[124:127]
	s_waitcnt lgkmcnt(0)
	v_mfma_f32_16x16x32_bf16 v[64:67], v[208:211], v[168:171], v[64:67]
	v_mfma_f32_16x16x32_bf16 v[128:131], v[208:211], v[176:179], v[128:131]
	s_sub_u32 s51, s51, 1
	s_cmp_lg_u32 s51, 0
	s_cbranch_scc1 .Lff2a_loop
	s_nop 7
	v_lshlrev_b32_e32 v246, 4, v135
	v_lshl_add_u32 v244, v134, 12, v246
	v_add_u32_e32 v245, 0x10000, v244
	global_load_dwordx4 v[148:151], v246, s[54:55]
	global_load_dwordx4 v[152:155], v246, s[54:55] offset:64
	global_load_dwordx4 v[156:159], v246, s[54:55] offset:128
	global_load_dwordx4 v[160:163], v246, s[54:55] offset:192
	global_load_dwordx4 v[164:167], v246, s[54:55] offset:256
	global_load_dwordx4 v[168:171], v246, s[54:55] offset:320
	global_load_dwordx4 v[172:175], v246, s[54:55] offset:384
	global_load_dwordx4 v[176:179], v246, s[54:55] offset:448
	global_load_dwordx4 v[180:183], v246, s[54:55] offset:512
	global_load_dwordx4 v[184:187], v246, s[54:55] offset:576
	global_load_dwordx4 v[188:191], v246, s[54:55] offset:640
	global_load_dwordx4 v[192:195], v246, s[54:55] offset:704
	global_load_dwordx4 v[196:199], v246, s[54:55] offset:768
	global_load_dwordx4 v[200:203], v246, s[54:55] offset:832
	global_load_dwordx4 v[204:207], v246, s[54:55] offset:896
	global_load_dwordx4 v[208:211], v246, s[54:55] offset:960
	global_load_dwordx4 v[212:215], v244, s[52:53]
	global_load_dwordx4 v[216:219], v244, s[52:53] offset:64
	global_load_dwordx4 v[220:223], v244, s[52:53] offset:128
	global_load_dwordx4 v[224:227], v244, s[52:53] offset:192
	global_load_dwordx4 v[228:231], v244, s[52:53] offset:256
	global_load_dwordx4 v[232:235], v244, s[52:53] offset:320
	global_load_dwordx4 v[236:239], v244, s[52:53] offset:384
	global_load_dwordx4 v[240:243], v244, s[52:53] offset:448
	s_waitcnt vmcnt(4)
	v_fmac_f32_e32 v212, v148, v4
	v_fmac_f32_e32 v213, v149, v5
	v_fmac_f32_e32 v214, v150, v6
	v_fmac_f32_e32 v215, v151, v7
	v_fmac_f32_e32 v216, v152, v8
	v_fmac_f32_e32 v217, v153, v9
	v_fmac_f32_e32 v218, v154, v10
	v_fmac_f32_e32 v219, v155, v11
	v_fmac_f32_e32 v220, v156, v12
	v_fmac_f32_e32 v221, v157, v13
	v_fmac_f32_e32 v222, v158, v14
	v_fmac_f32_e32 v223, v159, v15
	v_fmac_f32_e32 v224, v160, v16
	v_fmac_f32_e32 v225, v161, v17
	v_fmac_f32_e32 v226, v162, v18
	v_fmac_f32_e32 v227, v163, v19
	global_store_dwordx4 v244, v[212:215], s[52:53]
	global_store_dwordx4 v244, v[216:219], s[52:53] offset:64
	global_store_dwordx4 v244, v[220:223], s[52:53] offset:128
	global_store_dwordx4 v244, v[224:227], s[52:53] offset:192
	global_load_dwordx4 v[212:215], v244, s[52:53] offset:512
	global_load_dwordx4 v[216:219], v244, s[52:53] offset:576
	global_load_dwordx4 v[220:223], v244, s[52:53] offset:640
	global_load_dwordx4 v[224:227], v244, s[52:53] offset:704
	s_waitcnt vmcnt(4)
	v_fmac_f32_e32 v228, v164, v20
	v_fmac_f32_e32 v229, v165, v21
	v_fmac_f32_e32 v230, v166, v22
	v_fmac_f32_e32 v231, v167, v23
	v_fmac_f32_e32 v232, v168, v24
	v_fmac_f32_e32 v233, v169, v25
	v_fmac_f32_e32 v234, v170, v26
	v_fmac_f32_e32 v235, v171, v27
	v_fmac_f32_e32 v236, v172, v28
	v_fmac_f32_e32 v237, v173, v29
	v_fmac_f32_e32 v238, v174, v30
	v_fmac_f32_e32 v239, v175, v31
	v_fmac_f32_e32 v240, v176, v32
	v_fmac_f32_e32 v241, v177, v33
	v_fmac_f32_e32 v242, v178, v34
	v_fmac_f32_e32 v243, v179, v35
	global_store_dwordx4 v244, v[228:231], s[52:53] offset:256
	global_store_dwordx4 v244, v[232:235], s[52:53] offset:320
	global_store_dwordx4 v244, v[236:239], s[52:53] offset:384
	global_store_dwordx4 v244, v[240:243], s[52:53] offset:448
	global_load_dwordx4 v[228:231], v244, s[52:53] offset:768
	global_load_dwordx4 v[232:235], v244, s[52:53] offset:832
	global_load_dwordx4 v[236:239], v244, s[52:53] offset:896
	global_load_dwordx4 v[240:243], v244, s[52:53] offset:960
	s_waitcnt vmcnt(4)
	v_fmac_f32_e32 v212, v180, v36
	v_fmac_f32_e32 v213, v181, v37
	v_fmac_f32_e32 v214, v182, v38
	v_fmac_f32_e32 v215, v183, v39
	v_fmac_f32_e32 v216, v184, v40
	v_fmac_f32_e32 v217, v185, v41
	v_fmac_f32_e32 v218, v186, v42
	v_fmac_f32_e32 v219, v187, v43
	v_fmac_f32_e32 v220, v188, v44
	v_fmac_f32_e32 v221, v189, v45
	v_fmac_f32_e32 v222, v190, v46
	v_fmac_f32_e32 v223, v191, v47
	v_fmac_f32_e32 v224, v192, v48
	v_fmac_f32_e32 v225, v193, v49
	v_fmac_f32_e32 v226, v194, v50
	v_fmac_f32_e32 v227, v195, v51
	global_store_dwordx4 v244, v[212:215], s[52:53] offset:512
	global_store_dwordx4 v244, v[216:219], s[52:53] offset:576
	global_store_dwordx4 v244, v[220:223], s[52:53] offset:640
	global_store_dwordx4 v244, v[224:227], s[52:53] offset:704
	global_load_dwordx4 v[212:215], v245, s[52:53]
	global_load_dwordx4 v[216:219], v245, s[52:53] offset:64
	global_load_dwordx4 v[220:223], v245, s[52:53] offset:128
	global_load_dwordx4 v[224:227], v245, s[52:53] offset:192
	s_waitcnt vmcnt(4)
	v_fmac_f32_e32 v228, v196, v52
	v_fmac_f32_e32 v229, v197, v53
	v_fmac_f32_e32 v230, v198, v54
	v_fmac_f32_e32 v231, v199, v55
	v_fmac_f32_e32 v232, v200, v56
	v_fmac_f32_e32 v233, v201, v57
	v_fmac_f32_e32 v234, v202, v58
	v_fmac_f32_e32 v235, v203, v59
	v_fmac_f32_e32 v236, v204, v60
	v_fmac_f32_e32 v237, v205, v61
	v_fmac_f32_e32 v238, v206, v62
	v_fmac_f32_e32 v239, v207, v63
	v_fmac_f32_e32 v240, v208, v64
	v_fmac_f32_e32 v241, v209, v65
	v_fmac_f32_e32 v242, v210, v66
	v_fmac_f32_e32 v243, v211, v67
	global_store_dwordx4 v244, v[228:231], s[52:53] offset:768
	global_store_dwordx4 v244, v[232:235], s[52:53] offset:832
	global_store_dwordx4 v244, v[236:239], s[52:53] offset:896
	global_store_dwordx4 v244, v[240:243], s[52:53] offset:960
	global_load_dwordx4 v[228:231], v245, s[52:53] offset:256
	global_load_dwordx4 v[232:235], v245, s[52:53] offset:320
	global_load_dwordx4 v[236:239], v245, s[52:53] offset:384
	global_load_dwordx4 v[240:243], v245, s[52:53] offset:448
	s_waitcnt vmcnt(4)
	v_fmac_f32_e32 v212, v148, v68
	v_fmac_f32_e32 v213, v149, v69
	v_fmac_f32_e32 v214, v150, v70
	v_fmac_f32_e32 v215, v151, v71
	v_fmac_f32_e32 v216, v152, v72
	v_fmac_f32_e32 v217, v153, v73
	v_fmac_f32_e32 v218, v154, v74
	v_fmac_f32_e32 v219, v155, v75
	v_fmac_f32_e32 v220, v156, v76
	v_fmac_f32_e32 v221, v157, v77
	v_fmac_f32_e32 v222, v158, v78
	v_fmac_f32_e32 v223, v159, v79
	v_fmac_f32_e32 v224, v160, v80
	v_fmac_f32_e32 v225, v161, v81
	v_fmac_f32_e32 v226, v162, v82
	v_fmac_f32_e32 v227, v163, v83
	global_store_dwordx4 v245, v[212:215], s[52:53]
	global_store_dwordx4 v245, v[216:219], s[52:53] offset:64
	global_store_dwordx4 v245, v[220:223], s[52:53] offset:128
	global_store_dwordx4 v245, v[224:227], s[52:53] offset:192
	global_load_dwordx4 v[212:215], v245, s[52:53] offset:512
	global_load_dwordx4 v[216:219], v245, s[52:53] offset:576
	global_load_dwordx4 v[220:223], v245, s[52:53] offset:640
	global_load_dwordx4 v[224:227], v245, s[52:53] offset:704
	s_waitcnt vmcnt(4)
	v_fmac_f32_e32 v228, v164, v84
	v_fmac_f32_e32 v229, v165, v85
	v_fmac_f32_e32 v230, v166, v86
	v_fmac_f32_e32 v231, v167, v87
	v_fmac_f32_e32 v232, v168, v88
	v_fmac_f32_e32 v233, v169, v89
	v_fmac_f32_e32 v234, v170, v90
	v_fmac_f32_e32 v235, v171, v91
	v_fmac_f32_e32 v236, v172, v92
	v_fmac_f32_e32 v237, v173, v93
	v_fmac_f32_e32 v238, v174, v94
	v_fmac_f32_e32 v239, v175, v95
	v_fmac_f32_e32 v240, v176, v96
	v_fmac_f32_e32 v241, v177, v97
	v_fmac_f32_e32 v242, v178, v98
	v_fmac_f32_e32 v243, v179, v99
	global_store_dwordx4 v245, v[228:231], s[52:53] offset:256
	global_store_dwordx4 v245, v[232:235], s[52:53] offset:320
	global_store_dwordx4 v245, v[236:239], s[52:53] offset:384
	global_store_dwordx4 v245, v[240:243], s[52:53] offset:448
	global_load_dwordx4 v[228:231], v245, s[52:53] offset:768
	global_load_dwordx4 v[232:235], v245, s[52:53] offset:832
	global_load_dwordx4 v[236:239], v245, s[52:53] offset:896
	global_load_dwordx4 v[240:243], v245, s[52:53] offset:960
	s_waitcnt vmcnt(4)
	v_fmac_f32_e32 v212, v180, v100
	v_fmac_f32_e32 v213, v181, v101
	v_fmac_f32_e32 v214, v182, v102
	v_fmac_f32_e32 v215, v183, v103
	v_fmac_f32_e32 v216, v184, v104
	v_fmac_f32_e32 v217, v185, v105
	v_fmac_f32_e32 v218, v186, v106
	v_fmac_f32_e32 v219, v187, v107
	v_fmac_f32_e32 v220, v188, v108
	v_fmac_f32_e32 v221, v189, v109
	v_fmac_f32_e32 v222, v190, v110
	v_fmac_f32_e32 v223, v191, v111
	v_fmac_f32_e32 v224, v192, v112
	v_fmac_f32_e32 v225, v193, v113
	v_fmac_f32_e32 v226, v194, v114
	v_fmac_f32_e32 v227, v195, v115
	global_store_dwordx4 v245, v[212:215], s[52:53] offset:512
	global_store_dwordx4 v245, v[216:219], s[52:53] offset:576
	global_store_dwordx4 v245, v[220:223], s[52:53] offset:640
	global_store_dwordx4 v245, v[224:227], s[52:53] offset:704
	s_waitcnt vmcnt(0)
	v_fmac_f32_e32 v228, v196, v116
	v_fmac_f32_e32 v229, v197, v117
	v_fmac_f32_e32 v230, v198, v118
	v_fmac_f32_e32 v231, v199, v119
	v_fmac_f32_e32 v232, v200, v120
	v_fmac_f32_e32 v233, v201, v121
	v_fmac_f32_e32 v234, v202, v122
	v_fmac_f32_e32 v235, v203, v123
	v_fmac_f32_e32 v236, v204, v124
	v_fmac_f32_e32 v237, v205, v125
	v_fmac_f32_e32 v238, v206, v126
	v_fmac_f32_e32 v239, v207, v127
	v_fmac_f32_e32 v240, v208, v128
	v_fmac_f32_e32 v241, v209, v129
	v_fmac_f32_e32 v242, v210, v130
	v_fmac_f32_e32 v243, v211, v131
	global_store_dwordx4 v245, v[228:231], s[52:53] offset:768
	global_store_dwordx4 v245, v[232:235], s[52:53] offset:832
	global_store_dwordx4 v245, v[236:239], s[52:53] offset:896
	global_store_dwordx4 v245, v[240:243], s[52:53] offset:960
.Lff2a_done:
	s_add_u32 s2, s94, 0x4510000
	s_addc_u32 s3, s95, 0
	s_add_u32 s4, s94, 0x1910000
	v_lshrrev_b32_e32 v0, 6, v144
	v_and_b32_e32 v83, 15, v144
	v_bfe_u32 v82, v144, 4, 2
	s_addc_u32 s5, s95, 0
	s_cmp_eq_u32 s74, s74
	v_lshlrev_b32_e32 v84, 7, v83
	v_bitop3_b32 v87, v82, v144, 7 bitop3:0x78
	v_lshl_or_b32 v85, v0, 5, v83
	v_lshlrev_b32_e32 v86, 3, v82
	s_cbranch_scc1 .LBB0_1088
	v_lshrrev_b32_e32 v8, 3, v144
	v_xor_b32_e32 v4, v8, v144
	v_mul_u32_u24_e32 v0, 0x1040, v8
	v_lshlrev_b32_e32 v0, 1, v0
	v_mov_b32_e32 v1, 0
	v_lshlrev_b32_e32 v4, 4, v4
	v_lshl_add_u64 v[2:3], s[2:3], 0, v[0:1]
	v_and_b32_e32 v4, 0x70, v4
	v_mov_b32_e32 v5, v1
	v_lshl_add_u64 v[64:65], v[2:3], 0, v[4:5]
	v_lshrrev_b32_e32 v2, 2, v144
	v_lshrrev_b32_e32 v3, 5, v144
	v_and_b32_e32 v2, 24, v2
	v_and_b32_e32 v3, 28, v3
	v_add_u32_e32 v2, v2, v3
	v_and_or_b32 v2, v8, 3, v2
	v_mul_u32_u24_e32 v2, 0x1040, v2
	v_lshlrev_b32_e32 v2, 1, v2
	v_mov_b32_e32 v3, v1
	v_lshl_add_u64 v[6:7], s[4:5], 0, v[2:3]
	v_and_b32_e32 v3, 7, v144
	v_bitop3_b32 v3, v82, v3, 4 bitop3:0x36
	v_lshlrev_b32_e32 v91, 4, v3
	s_load_dword s33, s[78:79], 0xc8
	v_bitop3_b32 v3, v8, 7, v144 bitop3:0x48
	v_lshlrev_b32_e32 v3, 4, v3
	v_lshl_add_u64 v[66:67], v[6:7], 0, v[4:5]
	v_lshlrev_b32_e32 v88, 4, v144
	v_lshrrev_b32_e32 v4, 1, v144
	s_movk_i32 s6, 0x1e0
	v_or_b32_e32 v0, v3, v0
	v_and_or_b32 v4, v4, s6, v83
	s_add_u32 s6, s94, 0x240000
	v_lshl_add_u64 v[68:69], s[94:95], 0, v[0:1]
	v_or_b32_e32 v0, v2, v3
	v_add_u32_e32 v94, 0, v88
	v_lshlrev_b32_e32 v89, 4, v87
	v_lshlrev_b32_e32 v90, 7, v4
	v_or_b32_e32 v92, 16, v85
	s_addc_u32 s7, s95, 0
	v_lshl_add_u64 v[70:71], s[94:95], 0, v[0:1]
	v_mov_b32_e32 v93, 0x104000
	v_add_u32_e32 v95, 0x4000, v94
	s_mov_b64 s[8:9], 0x41000
	v_add_u32_e32 v96, 0x1000, v94
	v_add_u32_e32 v97, 0x5000, v94
	s_mov_b64 s[10:11], 0x82000
	v_add_u32_e32 v98, 0x2000, v94
	v_add_u32_e32 v99, 0x6000, v94
	s_mov_b64 s[12:13], 0xc3000
	v_add_u32_e32 v100, 0x3000, v94
	v_add_u32_e32 v101, 0x7000, v94
	s_mov_b64 s[14:15], 0x4510080
	s_waitcnt lgkmcnt(0)
	s_mov_b64 s[16:17], 0x1910080
	s_mov_b64 s[18:19], 0x4551080
	s_mov_b64 s[20:21], 0x1951080
	s_mov_b64 s[22:23], 0x4592080
	s_mov_b64 s[24:25], 0x1992080
	s_mov_b64 s[26:27], 0x45d3080
	s_mov_b64 s[28:29], 0x19d3080
	s_mov_b32 s36, 0x3e0f83e1
	s_movk_i32 s37, 0xdf00
	s_movk_i32 s38, 0xff
	s_movk_i32 s39, 0xff00
	s_mov_b64 s[30:31], 0x5000
	s_mov_b32 s40, s74
	s_branch .LBB0_1066
